# decay folding + removed the now-unneeded s_nop 6 before the P write in the retention loop
# baseline (speedup 1.0000x reference)
; #define LAS __attribute__((address_space(3)))
; #define RT_BAR() do { asm volatile("s_waitcnt lgkmcnt(0)" ::: "memory"); __builtin_amdgcn_s_barrier(); asm volatile("" ::: "memory"); } while (0)
; #define RT_VRD(dst, g) do { _Pragma("unroll") for (int j_ = 0; j_ < 2; ++j_) { const int jj_ = 2 * ((g) & 1) + j_; dst[j_] = *(const LAS bf16x8*)(vb + ((g) >> 1) * 4096 + (((4 * (jj_ >> 1) + 2 * (jj_ & 1) + hh) << 4) ^ m4)); } } while (0)
; #define RT_VMM(src, g) do { _Pragma("unroll") for (int j_ = 0; j_ < 2; ++j_) { const int jj_ = 2 * ((g) & 1) + j_; oacc[(g) >> 1] = __builtin_amdgcn_mfma_f32_32x32x16_bf16(src[j_], pf[jj_ >> 1][jj_ & 1], oacc[(g) >> 1], 0, 0, 0); } } while (0)
; __device__ __forceinline__ void p2_ret(const Frame& F, ArgsP a, int layer) {
;     ...
;                   LAS unsigned char* pw = lds + RT_P + ((wr * 2 + wc) * 2) * 1024 + lane * 16;
;                   *(LAS u32x4*)pw = (u32x4){pk[0], pk[1], pk[2], pk[3]}; *(LAS u32x4*)(pw + 1024) = (u32x4){pk[4], pk[5], pk[6], pk[7]}; }
;                 RT_BAR();
;                 { bf16x8 pf[2][2];
; #pragma unroll
;                   for (int kb2 = 0; kb2 < 2; ++kb2)
; #pragma unroll
;                       for (int s = 0; s < 2; ++s) pf[kb2][s] = *(const LAS bf16x8*)(lds + RT_P + ((wr * 2 + kb2) * 2 + s) * 1024 + lane * 16);
;                   const LAS unsigned char* vb = lds + RT_V0 + bf * 32768 + (128 * wc + kap) * 128;
;     ...
;                   bf16x8 va[2], vc[2];
;                   RT_VRD(va, 0); __builtin_amdgcn_sched_barrier(0);
;                   RT_VRD(vc, 1); RT_VMM(va, 0); __builtin_amdgcn_sched_barrier(0);
;                   RT_VRD(va, 2); RT_VMM(vc, 1); __builtin_amdgcn_sched_barrier(0);
;                   RT_VRD(vc, 3); RT_VMM(va, 2); __builtin_amdgcn_sched_barrier(0);
;                   RT_VRD(va, 4); RT_VMM(vc, 3); __builtin_amdgcn_sched_barrier(0);
;                   RT_VRD(vc, 5); RT_VMM(va, 4); __builtin_amdgcn_sched_barrier(0);
;                   RT_VRD(va, 6); RT_VMM(vc, 5); __builtin_amdgcn_sched_barrier(0);
;                   RT_VRD(vc, 7); RT_VMM(va, 6); __builtin_amdgcn_sched_barrier(0);
;                   RT_VMM(vc, 7); __builtin_amdgcn_sched_barrier(0);
;     ...
;                 }
;                 asm volatile("s_waitcnt vmcnt(0)" ::: "memory");
;                 if (cv) { const CvU cu = cv_decode(a, F.ws, cvhi, layer); cv_store(cu, lane, cvv, cvsc); cvhi += cvs; }
.LBB0_387:
	v_lshlrev_b32_e32 v98, 4, v0
	v_add_u32_e32 v99, s83, v98
	ds_write_b128 v99, v[190:193]
	ds_write_b128 v99, v[194:197] offset:1024
	s_lshl_b32 s12, s80, 6
	s_sub_i32 s12, 0x800, s12
	s_add_i32 s12, s12, s82
	v_add_u32_e32 v250, s12, v98
	ds_read_b128 v[242:245], v246 offset:4096
	ds_read_b128 v[106:109], v247 offset:4096
	s_waitcnt lgkmcnt(5)
	v_mfma_f32_32x32x16_bf16 v[82:97], v[234:237], v[190:193], v[82:97]
	s_waitcnt lgkmcnt(4)
	v_mfma_f32_32x32x16_bf16 v[82:97], v[238:241], v[194:197], v[82:97]
	ds_read_b128 v[234:237], v246 offset:8192
	ds_read_b128 v[238:241], v247 offset:8192
	s_waitcnt lgkmcnt(3)
	v_mfma_f32_32x32x16_bf16 v[66:81], v[242:245], v[190:193], v[66:81]
	s_waitcnt lgkmcnt(2)
	v_mfma_f32_32x32x16_bf16 v[66:81], v[106:109], v[194:197], v[66:81]
	ds_read_b128 v[242:245], v246 offset:12288
	ds_read_b128 v[106:109], v247 offset:12288
	s_waitcnt lgkmcnt(3)
	v_mfma_f32_32x32x16_bf16 v[50:65], v[234:237], v[190:193], v[50:65]
	s_waitcnt lgkmcnt(2)
	v_mfma_f32_32x32x16_bf16 v[50:65], v[238:241], v[194:197], v[50:65]
	ds_read_b128 v[234:237], v248
	ds_read_b128 v[238:241], v249
	s_barrier
	ds_read_b128 v[98:101], v250
	ds_read_b128 v[102:105], v250 offset:1024
	s_waitcnt lgkmcnt(5)
	v_mfma_f32_32x32x16_bf16 v[34:49], v[242:245], v[190:193], v[34:49]
	s_waitcnt lgkmcnt(4)
	v_mfma_f32_32x32x16_bf16 v[34:49], v[106:109], v[194:197], v[34:49]
	ds_read_b128 v[242:245], v248 offset:4096
	ds_read_b128 v[106:109], v249 offset:4096
	s_waitcnt lgkmcnt(2)
	v_mfma_f32_32x32x16_bf16 v[82:97], v[234:237], v[98:101], v[82:97]
	v_mfma_f32_32x32x16_bf16 v[82:97], v[238:241], v[102:105], v[82:97]
	ds_read_b128 v[234:237], v248 offset:8192
	ds_read_b128 v[238:241], v249 offset:8192
	s_waitcnt lgkmcnt(3)
	v_mfma_f32_32x32x16_bf16 v[66:81], v[242:245], v[98:101], v[66:81]
	s_waitcnt lgkmcnt(2)
	v_mfma_f32_32x32x16_bf16 v[66:81], v[106:109], v[102:105], v[66:81]
	ds_read_b128 v[242:245], v248 offset:12288
	ds_read_b128 v[106:109], v249 offset:12288
	s_waitcnt lgkmcnt(3)
	v_mfma_f32_32x32x16_bf16 v[50:65], v[234:237], v[98:101], v[50:65]
	s_waitcnt lgkmcnt(2)
	v_mfma_f32_32x32x16_bf16 v[50:65], v[238:241], v[102:105], v[50:65]
	s_waitcnt lgkmcnt(1)
	v_mfma_f32_32x32x16_bf16 v[34:49], v[242:245], v[98:101], v[34:49]
	s_waitcnt lgkmcnt(0)
	v_mfma_f32_32x32x16_bf16 v[34:49], v[106:109], v[102:105], v[34:49]
	s_waitcnt vmcnt(0)
	s_and_b64 vcc, exec, s[38:39]
	s_cbranch_vccnz .LBB0_357
	s_ashr_i32 s14, s36, 1
	s_cmpk_lt_i32 s14, 0x400
	s_cselect_b64 s[4:5], -1, 0
	s_mov_b64 s[70:71], 0
	s_and_b64 vcc, exec, s[4:5]
	s_cbranch_vccnz .LBB0_394
	s_mov_b64 s[46:47], -1
	s_cmpk_gt_u32 s14, 0x13ff
	s_mov_b64 s[6:7], -1
	s_cbranch_scc0 .LBB0_391
	s_add_i32 s12, s14, 0xffffec00
	s_mov_b64 s[6:7], 0
